# NSA tile-scan loops read posmax[j] with scalar loads instead of waited vector loads
# speedup vs baseline: 1.0470x; 1.0035x over previous
;   DI bool farj(int j) const { return (j * 64 + 63 < q0) && (pqmin - posmax[j] >= 799); }
;   DI bool farj(int j) const { return (j * 64 + 63 < q0) && (pqmin - posmax[j] >= 799); }
;   DI int next(int t) const { for (int j = t + 1; j < 128; ++j) if (inu(j) && farj(j)) return j; return -1; }
;   DI bool inu(int j) const {
;     unsigned long long a = (ulo >> (j & 63)) & (j < 64 ? 1ull : 0ull);
;     unsigned long long b = (uhi >> (j & 63)) & (j >= 64 ? 1ull : 0ull);
;     return (a | b) != 0ull;
;   }
;   DI bool mine(int j) const {
;     unsigned long long a = (mlo >> (j & 63)) & (j < 64 ? 1ull : 0ull);
;     unsigned long long b = (mhi >> (j & 63)) & (j >= 64 ? 1ull : 0ull);
;     return (a | b) != 0ull;
;   }
;   DI int next(int t) const { for (int j = t + 1; j < 128; ++j) if (inu(j) && !farj(j)) return j; return -1; }
.LBB0_654:
	s_add_i32 s36, s26, -1
	s_add_i32 s37, s26, -2
	s_lshr_b64 s[10:11], s[14:15], s36
	s_cmp_lt_i32 s37, 63
	s_cselect_b64 s[12:13], -1, 0
	v_cndmask_b32_e64 v0, 0, 1, s[12:13]
	v_and_b32_e32 v0, s10, v0
	s_lshr_b64 s[10:11], s[52:53], s36
	s_cmp_gt_i32 s37, 62
	s_cselect_b64 s[12:13], -1, 0
	v_cndmask_b32_e64 v2, 0, 1, s[12:13]
	v_and_b32_e32 v2, s10, v2
	v_or_b32_e32 v0, v2, v0
	v_cmp_eq_u64_e32 vcc, 0, v[0:1]
	s_mov_b64 s[10:11], -1
	s_mov_b64 s[12:13], -1
	s_cbranch_vccnz .LBB0_657
	s_sub_i32 s37, s35, 64
	s_mov_b64 s[12:13], 0
	s_cmp_lt_i32 s37, s34
	s_mov_b32 s46, s36
	s_cbranch_scc0 .LBB0_657
	s_load_dword s12, s[0:1], -0x4
	s_add_i32 s46, s27, 1
	s_waitcnt vmcnt(0) lgkmcnt(0)
	v_subrev_u32_e32 v0, s12, v151
	v_cmp_lt_i32_e64 s[12:13], s93, v0
.LBB0_657:
	s_and_b64 vcc, exec, s[12:13]
	s_cbranch_vccz .LBB0_653
	s_add_i32 s27, s27, 2
	s_lshr_b64 s[10:11], s[14:15], s26
	s_cmp_lt_u32 s36, 63
	s_cselect_b64 s[12:13], -1, 0
	v_cndmask_b32_e64 v0, 0, 1, s[12:13]
	v_and_b32_e32 v0, s10, v0
	s_lshr_b64 s[10:11], s[52:53], s26
	s_cmp_gt_u32 s36, 62
	s_cselect_b64 s[12:13], -1, 0
	v_cndmask_b32_e64 v2, 0, 1, s[12:13]
	v_and_b32_e32 v2, s10, v2
	v_or_b32_e32 v0, v2, v0
	v_cmp_ne_u64_e32 vcc, 0, v[0:1]
	s_mov_b64 s[10:11], -1
	s_mov_b64 s[12:13], -1
	s_cbranch_vccz .LBB0_661
	s_mov_b64 s[12:13], 0
	s_cmp_lt_i32 s35, s34
	s_mov_b32 s46, s26
	s_cbranch_scc0 .LBB0_661
	s_load_dword s12, s[0:1], 0x0
	s_mov_b32 s46, s27
	s_waitcnt vmcnt(0) lgkmcnt(0)
	v_subrev_u32_e32 v0, s12, v151
	v_cmp_lt_i32_e64 s[12:13], s93, v0

;   DI bool farj(int j) const { return (j * 64 + 63 < q0) && (pqmin - posmax[j] >= 799); }
;   DI bool farj(int j) const { return (j * 64 + 63 < q0) && (pqmin - posmax[j] >= 799); }
;   DI int next(int t) const { for (int j = t + 1; j < 128; ++j) if (inu(j) && farj(j)) return j; return -1; }
;   DI bool inu(int j) const {
;     unsigned long long a = (ulo >> (j & 63)) & (j < 64 ? 1ull : 0ull);
;     unsigned long long b = (uhi >> (j & 63)) & (j >= 64 ? 1ull : 0ull);
;     return (a | b) != 0ull;
;   }
;   DI bool mine(int j) const {
;     unsigned long long a = (mlo >> (j & 63)) & (j < 64 ? 1ull : 0ull);
;     unsigned long long b = (mhi >> (j & 63)) & (j >= 64 ? 1ull : 0ull);
;     return (a | b) != 0ull;
;   }
;   DI int next(int t) const { for (int j = t + 1; j < 128; ++j) if (inu(j) && !farj(j)) return j; return -1; }
.LBB0_674:
	s_add_i32 s64, s54, 1
	s_lshr_b64 s[12:13], s[14:15], s64
	s_cmp_lt_i32 s54, 63
	s_cselect_b64 s[36:37], -1, 0
	v_cndmask_b32_e64 v0, 0, 1, s[36:37]
	v_and_b32_e32 v0, s12, v0
	s_lshr_b64 s[12:13], s[52:53], s64
	s_cmp_gt_i32 s54, 62
	s_cselect_b64 s[36:37], -1, 0
	v_cndmask_b32_e64 v2, 0, 1, s[36:37]
	v_and_b32_e32 v2, s12, v2
	v_or_b32_e32 v0, v2, v0
	v_cmp_eq_u64_e32 vcc, 0, v[0:1]
	s_mov_b64 s[12:13], -1
	s_mov_b64 s[36:37], -1
	s_cbranch_vccnz .LBB0_677
	s_cmp_lt_i32 s47, s34
	s_mov_b64 s[36:37], 0
	s_cbranch_scc0 .LBB0_677
	s_lshl_b64 s[36:37], s[64:65], 2
	s_add_u32 s36, s44, s36
	s_addc_u32 s37, s45, s37
	s_load_dword s36, s[36:37], 0x0
	s_waitcnt vmcnt(0) lgkmcnt(0)
	v_subrev_u32_e32 v0, s36, v151
	v_cmp_lt_i32_e64 s[36:37], s93, v0

;   DI bool farj(int j) const { return (j * 64 + 63 < q0) && (pqmin - posmax[j] >= 799); }
;   DI int next(int t) const { for (int j = t + 1; j < 128; ++j) if (inu(j) && !farj(j)) return j; return -1; }
;   DI bool farj(int j) const { return (j * 64 + 63 < q0) && (pqmin - posmax[j] >= 799); }
;   DI bool inu(int j) const {
;     unsigned long long a = (ulo >> (j & 63)) & (j < 64 ? 1ull : 0ull);
;     unsigned long long b = (uhi >> (j & 63)) & (j >= 64 ? 1ull : 0ull);
;     return (a | b) != 0ull;
;   }
;   DI bool mine(int j) const {
;     unsigned long long a = (mlo >> (j & 63)) & (j < 64 ? 1ull : 0ull);
;     unsigned long long b = (mhi >> (j & 63)) & (j >= 64 ? 1ull : 0ull);
;     return (a | b) != 0ull;
;   }
;   DI int next(int t) const { for (int j = t + 1; j < 128; ++j) if (inu(j) && farj(j)) return j; return -1; }
.LBB0_750:
	s_add_i32 s26, s36, -1
	s_add_i32 s37, s36, -2
	s_lshr_b64 s[10:11], s[14:15], s26
	s_cmp_lt_i32 s37, 63
	s_cselect_b64 s[12:13], -1, 0
	v_cndmask_b32_e64 v0, 0, 1, s[12:13]
	v_and_b32_e32 v0, s10, v0
	s_lshr_b64 s[10:11], s[52:53], s26
	s_cmp_gt_i32 s37, 62
	s_cselect_b64 s[12:13], -1, 0
	v_cndmask_b32_e64 v2, 0, 1, s[12:13]
	v_and_b32_e32 v2, s10, v2
	v_or_b32_e32 v0, v2, v0
	v_cmp_eq_u64_e64 s[12:13], 0, v[0:1]
	s_and_b64 vcc, exec, s[12:13]
	s_cbranch_vccnz .LBB0_753
	s_sub_i32 s10, s27, 64
	s_cmp_ge_i32 s10, s34
	s_cselect_b64 s[12:13], -1, 0
	s_cmp_lt_i32 s10, s34
	s_cbranch_scc0 .LBB0_753
	s_load_dword s12, s[6:7], -0x4
	s_waitcnt vmcnt(0) lgkmcnt(0)
	v_subrev_u32_e32 v0, s12, v151
	v_cmp_gt_i32_e64 s[12:13], s89, v0
.LBB0_753:
	s_mov_b64 s[10:11], -1
	s_and_b64 vcc, exec, s[12:13]
	s_cbranch_vccz .LBB0_749
	s_lshr_b64 s[10:11], s[14:15], s36
	s_cmp_lt_u32 s26, 63
	s_cselect_b64 s[12:13], -1, 0
	v_cndmask_b32_e64 v0, 0, 1, s[12:13]
	v_and_b32_e32 v0, s10, v0
	s_lshr_b64 s[10:11], s[52:53], s36
	s_cmp_gt_u32 s26, 62
	s_cselect_b64 s[12:13], -1, 0
	v_cndmask_b32_e64 v2, 0, 1, s[12:13]
	v_and_b32_e32 v2, s10, v2
	v_or_b32_e32 v0, v2, v0
	v_cmp_ne_u64_e32 vcc, 0, v[0:1]
	v_cmp_eq_u64_e64 s[12:13], 0, v[0:1]
	s_cbranch_vccz .LBB0_757
	s_cmp_ge_i32 s27, s34
	s_cselect_b64 s[12:13], -1, 0
	s_cmp_lt_i32 s27, s34
	s_cbranch_scc0 .LBB0_757
	s_load_dword s12, s[6:7], 0x0
	s_waitcnt vmcnt(0) lgkmcnt(0)
	v_subrev_u32_e32 v0, s12, v151
	v_cmp_gt_i32_e64 s[12:13], s89, v0

;   DI bool farj(int j) const { return (j * 64 + 63 < q0) && (pqmin - posmax[j] >= 799); }
;   DI int next(int t) const { for (int j = t + 1; j < 128; ++j) if (inu(j) && !farj(j)) return j; return -1; }
;   DI bool farj(int j) const { return (j * 64 + 63 < q0) && (pqmin - posmax[j] >= 799); }
;   DI bool inu(int j) const {
;     unsigned long long a = (ulo >> (j & 63)) & (j < 64 ? 1ull : 0ull);
;     unsigned long long b = (uhi >> (j & 63)) & (j >= 64 ? 1ull : 0ull);
;     return (a | b) != 0ull;
;   }
;   DI bool mine(int j) const {
;     unsigned long long a = (mlo >> (j & 63)) & (j < 64 ? 1ull : 0ull);
;     unsigned long long b = (mhi >> (j & 63)) & (j >= 64 ? 1ull : 0ull);
;     return (a | b) != 0ull;
;   }
;   DI int next(int t) const { for (int j = t + 1; j < 128; ++j) if (inu(j) && farj(j)) return j; return -1; }
.LBB0_767:
	s_add_i32 s64, s36, 1
	s_lshr_b64 s[6:7], s[14:15], s64
	s_cmp_lt_i32 s36, 63
	s_cselect_b64 s[12:13], -1, 0
	v_cndmask_b32_e64 v0, 0, 1, s[12:13]
	v_and_b32_e32 v0, s6, v0
	s_lshr_b64 s[6:7], s[52:53], s64
	s_cmp_gt_i32 s36, 62
	s_cselect_b64 s[12:13], -1, 0
	v_cndmask_b32_e64 v2, 0, 1, s[12:13]
	v_and_b32_e32 v2, s6, v2
	v_or_b32_e32 v0, v2, v0
	v_cmp_eq_u64_e64 s[6:7], 0, v[0:1]
	s_and_b64 vcc, exec, s[6:7]
	s_cbranch_vccnz .LBB0_770
	s_cmp_ge_i32 s27, s34
	s_cselect_b64 s[6:7], -1, 0
	s_cmp_lt_i32 s27, s34
	s_cbranch_scc0 .LBB0_770
	s_lshl_b64 s[6:7], s[64:65], 2
	s_add_u32 s6, s44, s6
	s_addc_u32 s7, s45, s7
	s_load_dword s6, s[6:7], 0x0
	s_waitcnt vmcnt(0) lgkmcnt(0)
	v_subrev_u32_e32 v0, s6, v151
	v_cmp_gt_i32_e64 s[6:7], s89, v0
